# attn-B unit prologue: the 8 remaining K/V LDS-DMA loads in SGPR-base form (on top of merged waits)
# baseline (speedup 1.0000x reference)
.LBB0_673:
	s_lshl_b32 s16, s31, 8
	s_add_u32 s17, s18, s16
	s_addc_u32 s18, s19, 0
	s_add_u32 s78, s17, 0xf000000
	s_addc_u32 s88, s18, 0
	v_and_b32_e32 v2, 15, v36
	v_lshlrev_b32_e32 v38, 4, v159
	s_add_u32 s89, s26, s16
	v_lshlrev_b32_e32 v2, 4, v2
	s_addc_u32 s50, s27, 0
	s_lshl_b32 s17, s10, 13
	v_lshlrev_b32_e32 v5, 6, v159
	v_and_b32_e32 v6, 0x300, v38
	v_bitop3_b32 v2, v2, v36, 48 bitop3:0x78
	v_lshlrev_b32_e32 v37, 1, v159
	s_lshl_b32 s19, s3, 11
	v_and_b32_e32 v5, 0x700, v5
	v_or3_b32 v2, v6, v2, s17
	v_and_or_b32 v5, v38, 48, v5
	v_or_b32_e32 v140, s19, v2
	v_and_or_b32 v2, v37, 64, s17
	v_or3_b32 v142, v2, s19, v5
	v_or_b32_e32 v2, 0x400, v38
	v_lshrrev_b32_e32 v6, 8, v2
	s_movk_i32 s22, 0x700
	v_bitop3_b32 v6, v6, v36, 15 bitop3:0x78
	v_lshrrev_b32_e32 v2, 3, v2
	v_bitop3_b32 v7, v38, s22, v1 bitop3:0xc8
	v_lshlrev_b32_e32 v6, 4, v6
	v_and_b32_e32 v2, 0xc0, v2
	s_lshl_b32 s18, s13, 6
	s_sub_i32 s16, 2, s33
	s_sub_i32 s11, s11, s13
	v_or3_b32 v6, v6, v7, s17
	v_or_b32_e32 v2, s17, v2
	s_or_b32 s17, s19, s17
	s_cmp_lg_u32 0, -1
	v_or_b32_e32 v144, s19, v6
	s_and_b32 s100, s3, 1
	s_lshl_b32 s100, s100, 7
	v_xor_b32_e32 v140, s100, v140
	v_xor_b32_e32 v144, s100, v144
	v_or3_b32 v146, v2, s19, v5
	s_cselect_b32 s19, 0, 0
	s_add_i32 s51, s17, s19
	s_ashr_i32 s19, s18, 31
	s_add_i32 s91, s51, 0x10000
	s_lshl_b64 s[22:23], s[18:19], 8
	s_add_u32 s26, s89, s22
	s_addc_u32 s27, s50, s23
	s_add_u32 s28, s78, s22
	s_mov_b32 m0, s91
	s_addc_u32 s29, s88, s23
	global_load_lds_dwordx4 v140, s[26:27]
	s_mov_b32 m0, s51
	v_cvt_f32_i32_e32 v2, s16
	global_load_lds_dwordx4 v142, s[28:29]
	s_add_i32 m0, s51, 0x10400
	v_exp_f32_e32 v2, v2
	global_load_lds_dwordx4 v144, s[26:27]
	s_add_i32 m0, s51, 0x400
	s_add_u32 s19, s22, 0x4000
	global_load_lds_dwordx4 v146, s[28:29]
	s_addc_u32 s29, s23, 0
	s_add_u32 s26, s89, s19
	s_addc_u32 s27, s50, s29
	s_add_u32 s28, s78, s19
	s_addc_u32 s29, s88, s29
	s_add_i32 m0, s51, 0x14000
	s_add_i32 s19, s51, 0x4000
	global_load_lds_dwordx4 v140, s[26:27]
	s_mov_b32 m0, s19
	v_readfirstlane_b32 s16, v2
	global_load_lds_dwordx4 v142, s[28:29]
	s_add_i32 m0, s51, 0x14400
	v_mov_b32_e32 v141, v3
	global_load_lds_dwordx4 v144, s[26:27]
	s_add_i32 m0, s51, 0x4400
	s_cmp_eq_u32 s10, 1
	global_load_lds_dwordx4 v146, s[28:29]
	s_cselect_b64 s[26:27], -1, 0
	s_cmp_lg_u32 s10, 1
	s_cselect_b64 s[28:29], -1, 0
	s_cmp_lt_i32 s11, 2
	s_cselect_b64 s[38:39], -1, 0
	s_or_b64 s[28:29], s[28:29], s[38:39]
	v_mov_b32_e32 v143, v3
	v_mov_b32_e32 v145, v3
	v_mov_b32_e32 v147, v3
	s_and_b64 vcc, exec, s[28:29]
	s_cbranch_vccnz .LBB0_675
	s_add_u32 s19, s22, 0x8000
	s_addc_u32 s39, s23, 0
	s_add_u32 s22, s89, s19
	s_addc_u32 s23, s50, s39
	s_add_u32 s38, s78, s19
	s_addc_u32 s39, s88, s39
	s_cmp_lg_u32 0, -1
	s_cselect_b32 s19, 0, 0
	s_add_i32 s17, s19, s17
	s_add_i32 m0, s17, 0x18000
	s_add_i32 s19, s17, 0x8000
	global_load_lds_dwordx4 v140, s[22:23]
	s_mov_b32 m0, s19
	s_nop 0
	global_load_lds_dwordx4 v142, s[38:39]
	s_add_i32 m0, s17, 0x18400
	s_nop 0
	global_load_lds_dwordx4 v144, s[22:23]
	s_add_i32 m0, s17, 0x8400
	s_nop 0
	global_load_lds_dwordx4 v146, s[38:39]

.LBB0_688:
	s_add_i32 s16, s10, 2
	s_cmp_le_i32 s16, s11
	s_cselect_b64 s[22:23], -1, 0
	s_cmp_gt_i32 s16, s11
	s_cbranch_scc1 .LBB0_690
	s_add_i32 s13, s13, s16
	s_lshl_b32 s28, s13, 6
	s_ashr_i32 s29, s28, 31
	s_lshl_b64 s[28:29], s[28:29], 8
	s_add_u32 vcc_lo, s89, s28
	s_addc_u32 vcc_hi, s50, s29
	s_add_u32 s28, s78, s28
	s_addc_u32 s29, s88, s29
	s_lshl_b32 s13, s16, 14
	s_and_b32 s13, s13, 0xc000
	s_add_i32 s16, s91, s13
	s_add_i32 s13, s51, s13
	s_mov_b32 m0, s16
	s_nop 0
	global_load_lds_dwordx4 v140, vcc
	s_mov_b32 m0, s13
	s_nop 0
	global_load_lds_dwordx4 v142, s[28:29]
	s_add_i32 m0, s16, 0x400
	s_nop 0
	global_load_lds_dwordx4 v144, vcc
	s_add_i32 m0, s13, 0x400
	s_nop 0
	global_load_lds_dwordx4 v146, s[28:29]
